# v77 + running sum l combined across lane halves once per unit instead of per step; softmax alpha==1 fast path (sflow)
# speedup vs baseline: 1.0052x; 1.0052x over previous
; __device__ __forceinline__ bool softmax_pp(f32x16& p0, f32x16& p1, float& m_reg, float& l_reg, f32x16& negm, float& alpha, float& m_run, float dq, float nslope,
;                                            bf16x8& pa0, bf16x8& pa1, bf16x8& pa2, bf16x8& pa3) {
;     ...
;   for (int r = 0; r < 16; ++r) { p0[r] = __builtin_amdgcn_exp2f(p0[r]); p1[r] = __builtin_amdgcn_exp2f(p1[r]); }
;   float ps = 0;
; #pragma unroll
;   for (int r = 0; r < 16; ++r) ps += p0[r];
; #pragma unroll
;   for (int r = 0; r < 16; ++r) ps += p1[r];
;   { auto rr = __builtin_amdgcn_permlane32_swap(__float_as_uint(ps), __float_as_uint(ps), false, false);
;     ps = __uint_as_float(rr[0]) + __uint_as_float(rr[1]); }
;   l_reg = l_reg * alpha + ps;
.Lsf_common_0:
	v_max_f32_e32 v172, v172, v15
	v_exp_f32_e32 v2, v98
	v_exp_f32_e32 v3, v99
	v_exp_f32_e32 v4, v100
	v_exp_f32_e32 v5, v101
	v_exp_f32_e32 v12, v116
	v_exp_f32_e32 v6, v102
	v_exp_f32_e32 v7, v103
	v_add_f32_e32 v116, v3, v2
	v_exp_f32_e32 v8, v104
	v_add_f32_e32 v116, v4, v116
	v_exp_f32_e32 v9, v105
	v_add_f32_e32 v116, v5, v116
	v_exp_f32_e32 v100, v106
	v_add_f32_e32 v116, v6, v116
	v_exp_f32_e32 v102, v107
	v_add_f32_e32 v116, v7, v116
	v_exp_f32_e32 v104, v108
	v_add_f32_e32 v116, v8, v116
	v_exp_f32_e32 v106, v109
	v_add_f32_e32 v116, v9, v116
	v_exp_f32_e32 v108, v110
	v_add_f32_e32 v116, v100, v116
	v_exp_f32_e32 v110, v111
	v_add_f32_e32 v116, v102, v116
	v_exp_f32_e32 v112, v112
	v_add_f32_e32 v116, v104, v116
	v_exp_f32_e32 v113, v113
	v_add_f32_e32 v116, v106, v116
	v_exp_f32_e32 v10, v114
	v_add_f32_e32 v116, v108, v116
	v_exp_f32_e32 v11, v115
	v_add_f32_e32 v116, v110, v116
	v_add_f32_e32 v116, v112, v116
	v_exp_f32_e32 v13, v117
	v_add_f32_e32 v116, v113, v116
	v_exp_f32_e32 v14, v118
	v_add_f32_e32 v116, v10, v116
	v_exp_f32_e32 v15, v119
	v_add_f32_e32 v116, v11, v116
	v_exp_f32_e32 v98, v120
	v_add_f32_e32 v116, v12, v116
	v_exp_f32_e32 v99, v121
	v_add_f32_e32 v116, v13, v116
	v_exp_f32_e32 v101, v122
	v_add_f32_e32 v116, v14, v116
	v_exp_f32_e32 v103, v123
	v_add_f32_e32 v116, v15, v116
	v_exp_f32_e32 v105, v124
	v_add_f32_e32 v116, v98, v116
	v_exp_f32_e32 v107, v125
	v_add_f32_e32 v116, v99, v116
	v_exp_f32_e32 v109, v126
	v_add_f32_e32 v116, v101, v116
	v_exp_f32_e32 v111, v127
	v_add_f32_e32 v116, v103, v116
	v_exp_f32_e32 v114, v128
	v_add_f32_e32 v116, v105, v116
	v_exp_f32_e32 v115, v129
	v_add_f32_e32 v116, v107, v116
	v_add_f32_e32 v116, v109, v116
	v_add_f32_e32 v116, v111, v116
	v_add_f32_e32 v116, v114, v116
	v_add_f32_e32 v116, v115, v116
	v_cvt_pk_bf16_f32 v2, v2, v3
	v_cvt_pk_bf16_f32 v3, v4, v5
	v_cvt_pk_bf16_f32 v4, v6, v7
	v_cvt_pk_bf16_f32 v5, v8, v9
	v_cvt_pk_bf16_f32 v6, v100, v102
	v_cvt_pk_bf16_f32 v7, v104, v106
	v_cvt_pk_bf16_f32 v8, v108, v110
	v_cvt_pk_bf16_f32 v9, v112, v113
	v_cvt_pk_bf16_f32 v10, v10, v11
	v_cvt_pk_bf16_f32 v11, v12, v13
	v_cvt_pk_bf16_f32 v12, v14, v15
	v_cvt_pk_bf16_f32 v13, v98, v99
	v_cvt_pk_bf16_f32 v162, v101, v103
	v_cvt_pk_bf16_f32 v163, v105, v107
	v_cvt_pk_bf16_f32 v164, v109, v111
	v_cvt_pk_bf16_f32 v165, v114, v115
	v_add_f32_e32 v80, v80, v116
	s_branch .LBB0_375
.LBB0_369:
	v_max_f32_e32 v172, v172, v15
	v_exp_f32_e32 v2, v98
	v_exp_f32_e32 v3, v99
	v_exp_f32_e32 v4, v100
	v_exp_f32_e32 v5, v101
	v_exp_f32_e32 v12, v116
	v_exp_f32_e32 v6, v102
	v_exp_f32_e32 v7, v103
	v_add_f32_e32 v116, v3, v2
	v_exp_f32_e32 v8, v104
	v_add_f32_e32 v116, v4, v116
	v_exp_f32_e32 v9, v105
	v_add_f32_e32 v116, v5, v116
	v_exp_f32_e32 v100, v106
	v_add_f32_e32 v116, v6, v116
	v_exp_f32_e32 v102, v107
	v_add_f32_e32 v116, v7, v116
	v_exp_f32_e32 v104, v108
	v_add_f32_e32 v116, v8, v116
	v_exp_f32_e32 v106, v109
	v_add_f32_e32 v116, v9, v116
	v_exp_f32_e32 v108, v110
	v_add_f32_e32 v116, v100, v116
	v_exp_f32_e32 v110, v111
	v_add_f32_e32 v116, v102, v116
	v_exp_f32_e32 v112, v112
	v_add_f32_e32 v116, v104, v116
	v_exp_f32_e32 v113, v113
	v_add_f32_e32 v116, v106, v116
	v_exp_f32_e32 v10, v114
	v_add_f32_e32 v116, v108, v116
	v_exp_f32_e32 v11, v115
	v_add_f32_e32 v116, v110, v116
	v_add_f32_e32 v116, v112, v116
	v_exp_f32_e32 v13, v117
	v_add_f32_e32 v116, v113, v116
	v_exp_f32_e32 v14, v118
	v_add_f32_e32 v116, v10, v116
	v_exp_f32_e32 v15, v119
	v_add_f32_e32 v116, v11, v116
	v_exp_f32_e32 v98, v120
	v_add_f32_e32 v116, v12, v116
	v_exp_f32_e32 v99, v121
	v_add_f32_e32 v116, v13, v116
	v_exp_f32_e32 v101, v122
	v_add_f32_e32 v116, v14, v116
	v_exp_f32_e32 v103, v123
	v_add_f32_e32 v116, v15, v116
	v_exp_f32_e32 v105, v124
	v_add_f32_e32 v116, v98, v116
	v_exp_f32_e32 v107, v125
	v_add_f32_e32 v116, v99, v116
	v_exp_f32_e32 v109, v126
	v_add_f32_e32 v116, v101, v116
	v_exp_f32_e32 v111, v127
	v_add_f32_e32 v116, v103, v116
	v_exp_f32_e32 v114, v128
	v_add_f32_e32 v116, v105, v116
	v_exp_f32_e32 v115, v129
	v_add_f32_e32 v116, v107, v116
	v_add_f32_e32 v116, v109, v116
	v_add_f32_e32 v116, v111, v116
	v_add_f32_e32 v116, v114, v116
	v_add_f32_e32 v116, v115, v116
	v_cvt_pk_bf16_f32 v2, v2, v3
	v_cvt_pk_bf16_f32 v3, v4, v5
	v_cvt_pk_bf16_f32 v4, v6, v7
	v_cvt_pk_bf16_f32 v5, v8, v9
	v_cvt_pk_bf16_f32 v6, v100, v102
	v_cvt_pk_bf16_f32 v7, v104, v106
	v_cvt_pk_bf16_f32 v8, v108, v110
	v_cvt_pk_bf16_f32 v9, v112, v113
	v_cvt_pk_bf16_f32 v10, v10, v11
	v_cvt_pk_bf16_f32 v11, v12, v13
	v_cvt_pk_bf16_f32 v12, v14, v15
	v_cvt_pk_bf16_f32 v13, v98, v99
	v_cvt_pk_bf16_f32 v162, v101, v103
	v_cvt_pk_bf16_f32 v163, v105, v107
	v_cvt_pk_bf16_f32 v164, v109, v111
	v_cvt_pk_bf16_f32 v165, v114, v115
	v_fma_f32 v80, v80, v0, v116
	s_branch .LBB0_371

; __device__ __forceinline__ bool softmax_pp(f32x16& p0, f32x16& p1, float& m_reg, float& l_reg, f32x16& negm, float& alpha, float& m_run, float dq, float nslope,
;                                            bf16x8& pa0, bf16x8& pa1, bf16x8& pa2, bf16x8& pa3) {
;     ...
;   for (int r = 0; r < 16; ++r) { p0[r] = __builtin_amdgcn_exp2f(p0[r]); p1[r] = __builtin_amdgcn_exp2f(p1[r]); }
;   float ps = 0;
; #pragma unroll
;   for (int r = 0; r < 16; ++r) ps += p0[r];
; #pragma unroll
;   for (int r = 0; r < 16; ++r) ps += p1[r];
;   { auto rr = __builtin_amdgcn_permlane32_swap(__float_as_uint(ps), __float_as_uint(ps), false, false);
;     ps = __uint_as_float(rr[0]) + __uint_as_float(rr[1]); }
;   l_reg = l_reg * alpha + ps;
.LBB0_384:
	v_max_f32_e32 v172, v172, v15
	v_exp_f32_e32 v2, v98
	v_exp_f32_e32 v3, v99
	v_exp_f32_e32 v4, v100
	v_exp_f32_e32 v5, v101
	v_exp_f32_e32 v12, v116
	v_exp_f32_e32 v6, v102
	v_exp_f32_e32 v7, v103
	v_add_f32_e32 v116, v3, v2
	v_exp_f32_e32 v8, v104
	v_add_f32_e32 v116, v4, v116
	v_exp_f32_e32 v9, v105
	v_add_f32_e32 v116, v5, v116
	v_exp_f32_e32 v100, v106
	v_add_f32_e32 v116, v6, v116
	v_exp_f32_e32 v102, v107
	v_add_f32_e32 v116, v7, v116
	v_exp_f32_e32 v104, v108
	v_add_f32_e32 v116, v8, v116
	v_exp_f32_e32 v106, v109
	v_add_f32_e32 v116, v9, v116
	v_exp_f32_e32 v108, v110
	v_add_f32_e32 v116, v100, v116
	v_exp_f32_e32 v110, v111
	v_add_f32_e32 v116, v102, v116
	v_exp_f32_e32 v112, v112
	v_add_f32_e32 v116, v104, v116
	v_exp_f32_e32 v113, v113
	v_add_f32_e32 v116, v106, v116
	v_exp_f32_e32 v10, v114
	v_add_f32_e32 v116, v108, v116
	v_exp_f32_e32 v11, v115
	v_add_f32_e32 v116, v110, v116
	v_add_f32_e32 v116, v112, v116
	v_exp_f32_e32 v13, v117
	v_add_f32_e32 v116, v113, v116
	v_exp_f32_e32 v14, v118
	v_add_f32_e32 v116, v10, v116
	v_exp_f32_e32 v15, v119
	v_add_f32_e32 v116, v11, v116
	v_exp_f32_e32 v98, v120
	v_add_f32_e32 v116, v12, v116
	v_exp_f32_e32 v99, v121
	v_add_f32_e32 v116, v13, v116
	v_exp_f32_e32 v101, v122
	v_add_f32_e32 v116, v14, v116
	v_exp_f32_e32 v103, v123
	v_add_f32_e32 v116, v15, v116
	v_exp_f32_e32 v105, v124
	v_add_f32_e32 v116, v98, v116
	v_exp_f32_e32 v107, v125
	v_add_f32_e32 v116, v99, v116
	v_exp_f32_e32 v109, v126
	v_add_f32_e32 v116, v101, v116
	v_exp_f32_e32 v111, v127
	v_add_f32_e32 v116, v103, v116
	v_exp_f32_e32 v114, v128
	v_add_f32_e32 v116, v105, v116
	v_exp_f32_e32 v115, v129
	v_add_f32_e32 v116, v107, v116
	v_add_f32_e32 v116, v109, v116
	v_add_f32_e32 v116, v111, v116
	v_add_f32_e32 v116, v114, v116
	v_add_f32_e32 v116, v115, v116
	v_cvt_pk_bf16_f32 v2, v2, v3
	v_cvt_pk_bf16_f32 v3, v4, v5
	v_cvt_pk_bf16_f32 v4, v6, v7
	v_cvt_pk_bf16_f32 v5, v8, v9
	v_cvt_pk_bf16_f32 v6, v100, v102
	v_cvt_pk_bf16_f32 v7, v104, v106
	v_cvt_pk_bf16_f32 v8, v108, v110
	v_cvt_pk_bf16_f32 v9, v112, v113
	v_cvt_pk_bf16_f32 v10, v10, v11
	v_cvt_pk_bf16_f32 v11, v12, v13
	v_cvt_pk_bf16_f32 v12, v14, v15
	v_cvt_pk_bf16_f32 v13, v98, v99
	v_cvt_pk_bf16_f32 v162, v101, v103
	v_cvt_pk_bf16_f32 v163, v105, v107
	v_cvt_pk_bf16_f32 v164, v109, v111
	v_cvt_pk_bf16_f32 v165, v114, v115
	v_fma_f32 v80, v80, v0, v116

; __device__ __forceinline__ void attn_unit_pp(int b, int h, int qb, int par, const bf16_t* __restrict__ QBp, const bf16_t* __restrict__ KBp, const bf16_t* __restrict__ VBp, ...
;     ...
;   _Pragma("nounroll") for (int j = 0; j < n; j += 2) { PP_STEP(j, 0); PP_STEP(j + 1, 1); }
;   if (live) pv_d0(o, vb0 + (int)SHM_V, pa0, pa1, pa2, pa3);
;   if (g == 0) __syncthreads();
;   __builtin_amdgcn_s_setprio(0);
;     ...
;   if (hi == 0) li_l[r32] = l_reg; asm volatile("s_waitcnt lgkmcnt(0)" ::: "memory");
.LBB0_403:
	v_mov_b32_e32 v14, v80
	s_nop 1
	v_permlane32_swap_b32_e32 v80, v14
	v_add_f32_e32 v80, v80, v14
	s_andn2_b64 vcc, exec, s[14:15]
	s_cbranch_vccnz .LBB0_409
	s_andn2_b64 vcc, exec, s[12:13]
	s_cbranch_vccz .LBB0_410
